# speedup vs baseline: 1.0000x; 1.0000x over previous
; #define KSWZ(row, colB) ((row) * 256 + ((colB) ^ (KSWZF(row) << 4)))
; #define SBAR() __builtin_amdgcn_sched_barrier(0)
; template <int H> __device__ __forceinline__ void qkt_half(f32x16& pz, const char* Ks, const bf16x8* qr, int r32, int hi) {
;   bf16x8 kf[8];
; #pragma unroll
;   for (int d0 = 0; d0 < 8; ++d0) { const int cb = (d0 * 16 + hi * 8) * 2; kf[d0] = *reinterpret_cast<const bf16x8*>(Ks + KSWZ(32 * H + r32, cb)); }
;   asm volatile("s_waitcnt lgkmcnt(0)" ::: "memory"); SBAR();
;   f32x16 pb = {};
; #pragma unroll
;   for (int d0 = 0; d0 < 8; d0 += 2) {
;     pz = __builtin_amdgcn_mfma_f32_32x32x16_bf16(kf[d0], qr[d0], pz, 0, 0, 0);
;     pb = __builtin_amdgcn_mfma_f32_32x32x16_bf16(kf[d0 + 1], qr[d0 + 1], pb, 0, 0, 0); }
; #pragma unroll
;   for (int r = 0; r < 16; ++r) pz[r] += pb[r];
; }
; template <int MODE>
; __device__ __forceinline__ void nsa_single(const Params& p, const LaneId& L, int q0, int g, int ntiles, int first, char* smem, const bf16x8* qr, float gate, f32x16* o) {
;     ...
;     int pb = row, lo, hl; float badd = 0.f;
;     if (MODE == 1) { const int j = row >> 6; lo = NEG; const bool fl = ((mysel[j >> 5] >> (j & 31)) & 1u) != 0u;
;       if (row == q0) hl = fl ? (L.tq - pb) : NEG; else { hl = 1000; badd = fl ? 0.f : -INFINITY; } }
;     else { lo = L.tq - 512 - pb; hl = L.tq - pb; }
;     constexpr float C = 0.08838834764831845f * LOG2E;
;     const float A1 = L.sl2; const float B1 = L.sl2 * (float)(pb - L.tq) + A1 * (float)(4 * L.hi) + badd;
;     const int lo2 = lo - 4 * L.hi, hl2 = hl - 4 * L.hi;
;     const bool nomask = __all(lo2 < 0 && hl2 >= 63);
.LBB0_318:
	s_ashr_i32 s3, s2, 5
	v_lshl_add_u32 v68, s3, 2, v149
	ds_read_b32 v72, v68
	s_lshl_b32 s3, s2, 6
	s_and_b32 s2, s2, 31
	v_sub_u32_e32 v74, s3, v148
	v_cvt_f32_i32_e32 v74, v74
	s_waitcnt lgkmcnt(0)
	v_bfe_u32 v72, v72, s2, 1
	s_cmp_eq_u32 s3, s5
	v_subrev_u32_e32 v73, s3, v148
	v_cmp_eq_u32_e32 vcc, 0, v72
	v_fma_f32 v74, v138, v74, v151
	s_nop 1
	v_cndmask_b32_e32 v72, v73, v190, vcc
	v_cndmask_b32_e32 v73, 0, v183, vcc
	s_cselect_b64 vcc, -1, 0
	v_cndmask_b32_e32 v72, v191, v72, vcc
	v_cndmask_b32_e64 v73, v73, 0, vcc
	v_sub_u32_e32 v163, v72, v150
	v_add_f32_e32 v140, v74, v73
	v_cmp_lt_i32_e32 vcc, 62, v163
	s_nop 3
	s_cmp_lg_u64 vcc, exec
	s_cselect_b64 s[98:99], -1, 0
	v_add_f32_e32 v243, 0x41000000, v165
	v_mov_b32_e32 v250, v140
	s_setprio 1
	s_waitcnt lgkmcnt(7)
	v_mfma_f32_32x32x16_bf16 v[68:83], v[84:87], v[100:103], v[226:241]
	v_add_u32_e32 v249, v242, v153
	ds_read_b128 v[84:87], v249 offset:8192
	s_waitcnt lgkmcnt(7)
	v_mfma_f32_32x32x16_bf16 v[68:83], v[88:91], v[104:107], v[68:83]
	v_add_u32_e32 v251, v242, v154
	ds_read_b128 v[88:91], v251 offset:8192
	s_waitcnt lgkmcnt(7)
	v_mfma_f32_32x32x16_bf16 v[68:83], v[92:95], v[108:111], v[68:83]
	v_add_u32_e32 v249, v242, v155
	ds_read_b128 v[92:95], v249 offset:8192
	s_waitcnt lgkmcnt(7)
	v_mfma_f32_32x32x16_bf16 v[68:83], v[96:99], v[112:115], v[68:83]
	v_add_u32_e32 v251, v242, v156
	ds_read_b128 v[96:99], v251 offset:8192
	s_waitcnt lgkmcnt(7)
	v_mfma_f32_32x32x16_bf16 v[68:83], v[194:197], v[116:119], v[68:83]
	v_add_u32_e32 v249, v242, v157
	ds_read_b128 v[194:197], v249 offset:8192
	s_waitcnt lgkmcnt(7)
	v_mfma_f32_32x32x16_bf16 v[68:83], v[198:201], v[120:123], v[68:83]
	v_add_u32_e32 v251, v242, v158
	ds_read_b128 v[198:201], v251 offset:8192
	s_waitcnt lgkmcnt(7)
	v_mfma_f32_32x32x16_bf16 v[68:83], v[202:205], v[124:127], v[68:83]
	v_add_u32_e32 v249, v242, v159
	ds_read_b128 v[202:205], v249 offset:8192
	s_waitcnt lgkmcnt(7)
	v_mfma_f32_32x32x16_bf16 v[68:83], v[206:209], v[128:131], v[68:83]
	v_add_u32_e32 v251, v242, v160
	ds_read_b128 v[206:209], v251 offset:8192
	s_waitcnt lgkmcnt(7)
	v_mfma_f32_32x32x16_bf16 v[210:225], v[84:87], v[100:103], v[226:241]
	ds_read_b64_tr_b16 v[84:85], v248 offset:0
	ds_read_b64_tr_b16 v[86:87], v248 offset:2048
	s_waitcnt lgkmcnt(8)
	v_mfma_f32_32x32x16_bf16 v[210:225], v[88:91], v[104:107], v[210:225]
	ds_read_b64_tr_b16 v[88:89], v248 offset:4096
	ds_read_b64_tr_b16 v[90:91], v248 offset:6144
	s_waitcnt lgkmcnt(9)
	v_mfma_f32_32x32x16_bf16 v[210:225], v[92:95], v[108:111], v[210:225]
	ds_read_b64_tr_b16 v[92:93], v248 offset:512
	ds_read_b64_tr_b16 v[94:95], v248 offset:2560
	s_waitcnt lgkmcnt(10)
	v_mfma_f32_32x32x16_bf16 v[210:225], v[96:99], v[112:115], v[210:225]
	ds_read_b64_tr_b16 v[96:97], v248 offset:4608
	ds_read_b64_tr_b16 v[98:99], v248 offset:6656
	s_waitcnt lgkmcnt(11)
	v_mfma_f32_32x32x16_bf16 v[210:225], v[194:197], v[116:119], v[210:225]
	ds_read_b64_tr_b16 v[194:195], v248 offset:1024
	ds_read_b64_tr_b16 v[196:197], v248 offset:3072
	s_waitcnt lgkmcnt(12)
	v_mfma_f32_32x32x16_bf16 v[210:225], v[198:201], v[120:123], v[210:225]
	ds_read_b64_tr_b16 v[198:199], v248 offset:5120
	ds_read_b64_tr_b16 v[200:201], v248 offset:7168
	s_waitcnt lgkmcnt(13)
	v_mfma_f32_32x32x16_bf16 v[210:225], v[202:205], v[124:127], v[210:225]
	ds_read_b64_tr_b16 v[202:203], v248 offset:1536
	ds_read_b64_tr_b16 v[204:205], v248 offset:3584
	s_waitcnt lgkmcnt(14)
	v_mfma_f32_32x32x16_bf16 v[210:225], v[206:209], v[128:131], v[210:225]
	ds_read_b64_tr_b16 v[206:207], v248 offset:5632
	ds_read_b64_tr_b16 v[208:209], v248 offset:7680
	s_setprio 0
	v_fmamk_f32 v251, v138, 0x42000000, v140
	s_and_b64 vcc, exec, s[98:99]
	s_cbranch_vccz .Lsel_nm
	v_cmp_lt_i32_e32 vcc, -1, v163
	v_cmp_lt_i32_e64 s[10:11], 0, v163
	v_cmp_lt_i32_e64 s[12:13], 1, v163
	v_cmp_lt_i32_e64 s[2:3], 2, v163
	s_nop 0
	v_cndmask_b32_e32 v68, v183, v68, vcc
	v_cndmask_b32_e64 v69, v183, v69, s[10:11]
	v_cndmask_b32_e64 v70, v183, v70, s[12:13]
	v_cndmask_b32_e64 v71, v183, v71, s[2:3]
	v_cmp_lt_i32_e32 vcc, 7, v163
	v_cmp_lt_i32_e64 s[10:11], 8, v163
	v_cmp_lt_i32_e64 s[12:13], 9, v163
	v_cmp_lt_i32_e64 s[2:3], 10, v163
	s_nop 0
	v_cndmask_b32_e32 v72, v183, v72, vcc
	v_cndmask_b32_e64 v73, v183, v73, s[10:11]
	v_cndmask_b32_e64 v74, v183, v74, s[12:13]
	v_cndmask_b32_e64 v75, v183, v75, s[2:3]
	v_cmp_lt_i32_e32 vcc, 15, v163
	v_cmp_lt_i32_e64 s[10:11], 16, v163
	v_cmp_lt_i32_e64 s[12:13], 17, v163
	v_cmp_lt_i32_e64 s[2:3], 18, v163
	s_nop 0
	v_cndmask_b32_e32 v76, v183, v76, vcc
	v_cndmask_b32_e64 v77, v183, v77, s[10:11]
	v_cndmask_b32_e64 v78, v183, v78, s[12:13]
	v_cndmask_b32_e64 v79, v183, v79, s[2:3]
	v_cmp_lt_i32_e32 vcc, 23, v163
	v_cmp_lt_i32_e64 s[10:11], 24, v163
	v_cmp_lt_i32_e64 s[12:13], 25, v163
	v_cmp_lt_i32_e64 s[2:3], 26, v163
	s_nop 0
	v_cndmask_b32_e32 v80, v183, v80, vcc
	v_cndmask_b32_e64 v81, v183, v81, s[10:11]
	v_cndmask_b32_e64 v82, v183, v82, s[12:13]
	v_cndmask_b32_e64 v83, v183, v83, s[2:3]
	v_cmp_lt_i32_e32 vcc, 31, v163
	v_cmp_lt_i32_e64 s[10:11], 32, v163
	v_cmp_lt_i32_e64 s[12:13], 33, v163
	v_cmp_lt_i32_e64 s[2:3], 34, v163
	s_nop 0
	v_cndmask_b32_e32 v210, v183, v210, vcc
	v_cndmask_b32_e64 v211, v183, v211, s[10:11]
	v_cndmask_b32_e64 v212, v183, v212, s[12:13]
	v_cndmask_b32_e64 v213, v183, v213, s[2:3]
	v_cmp_lt_i32_e32 vcc, 39, v163
	v_cmp_lt_i32_e64 s[10:11], 40, v163
	v_cmp_lt_i32_e64 s[12:13], 41, v163
	v_cmp_lt_i32_e64 s[2:3], 42, v163
	s_nop 0
	v_cndmask_b32_e32 v214, v183, v214, vcc
	v_cndmask_b32_e64 v215, v183, v215, s[10:11]
	v_cndmask_b32_e64 v216, v183, v216, s[12:13]
	v_cndmask_b32_e64 v217, v183, v217, s[2:3]
	v_cmp_lt_i32_e32 vcc, 47, v163
	v_cmp_lt_i32_e64 s[10:11], 48, v163
	v_cmp_lt_i32_e64 s[12:13], 49, v163
	v_cmp_lt_i32_e64 s[2:3], 50, v163
	s_nop 0
	v_cndmask_b32_e32 v218, v183, v218, vcc
	v_cndmask_b32_e64 v219, v183, v219, s[10:11]
	v_cndmask_b32_e64 v220, v183, v220, s[12:13]
	v_cndmask_b32_e64 v221, v183, v221, s[2:3]
	v_cmp_lt_i32_e32 vcc, 55, v163
	v_cmp_lt_i32_e64 s[10:11], 56, v163
	v_cmp_lt_i32_e64 s[12:13], 57, v163
	v_cmp_lt_i32_e64 s[2:3], 58, v163
	s_nop 0
	v_cndmask_b32_e32 v222, v183, v222, vcc
	v_cndmask_b32_e64 v223, v183, v223, s[10:11]
	v_cndmask_b32_e64 v224, v183, v224, s[12:13]
	v_cndmask_b32_e64 v225, v183, v225, s[2:3]

; #define SBAR() __builtin_amdgcn_sched_barrier(0)
; #define TRQ(D0) const s16x4 l0_##D0 = tr_read<v_rd_off(D0, 2 * H, 0)>(vb), h0_##D0 = tr_read<v_rd_off(D0, 2 * H, 1)>(vb), \
;                             l1_##D0 = tr_read<v_rd_off(D0, 2 * H + 1, 0)>(vb), h1_##D0 = tr_read<v_rd_off(D0, 2 * H + 1, 1)>(vb)
; template <int H> __device__ __forceinline__ void pv_half(f32x16* o, int vb, bf16x8 paA, bf16x8 paB) {
;     ...
;   TRQ(0); TRQ(1); TRQ(2); TRQ(3);
;     ...
;   asm volatile("s_waitcnt lgkmcnt(0)" ::: "memory"); SBAR();
;     ...
;   o[0] = __builtin_amdgcn_mfma_f32_32x32x16_bf16(paA, PK(l0_0, h0_0), o[0], 0, 0, 0);
;   o[1] = __builtin_amdgcn_mfma_f32_32x32x16_bf16(paA, PK(l0_1, h0_1), o[1], 0, 0, 0);
;   o[2] = __builtin_amdgcn_mfma_f32_32x32x16_bf16(paA, PK(l0_2, h0_2), o[2], 0, 0, 0);
;   o[3] = __builtin_amdgcn_mfma_f32_32x32x16_bf16(paA, PK(l0_3, h0_3), o[3], 0, 0, 0);
;   o[0] = __builtin_amdgcn_mfma_f32_32x32x16_bf16(paB, PK(l1_0, h1_0), o[0], 0, 0, 0);
;   o[1] = __builtin_amdgcn_mfma_f32_32x32x16_bf16(paB, PK(l1_1, h1_1), o[1], 0, 0, 0);
;   o[2] = __builtin_amdgcn_mfma_f32_32x32x16_bf16(paB, PK(l1_2, h1_2), o[2], 0, 0, 0);
;   o[3] = __builtin_amdgcn_mfma_f32_32x32x16_bf16(paB, PK(l1_3, h1_3), o[3], 0, 0, 0);
;     ...
; }
.Lsel_nr:
	v_sub_f32_e32 v242, v250, v165
	v_sub_f32_e32 v249, v251, v165
	s_nop 0
	v_fmamk_f32 v68, v68, 0x3e0293ee, v242
	v_fmamk_f32 v69, v69, 0x3e0293ee, v242
	v_fmamk_f32 v70, v70, 0x3e0293ee, v242
	v_fmamk_f32 v71, v71, 0x3e0293ee, v242
	v_fmamk_f32 v72, v72, 0x3e0293ee, v242
	v_fmamk_f32 v73, v73, 0x3e0293ee, v242
	v_fmamk_f32 v74, v74, 0x3e0293ee, v242
	v_fmamk_f32 v75, v75, 0x3e0293ee, v242
	v_fmamk_f32 v76, v76, 0x3e0293ee, v242
	v_fmamk_f32 v77, v77, 0x3e0293ee, v242
	v_fmamk_f32 v78, v78, 0x3e0293ee, v242
	v_fmamk_f32 v79, v79, 0x3e0293ee, v242
	v_fmamk_f32 v80, v80, 0x3e0293ee, v242
	v_fmamk_f32 v81, v81, 0x3e0293ee, v242
	v_fmamk_f32 v82, v82, 0x3e0293ee, v242
	v_fmamk_f32 v83, v83, 0x3e0293ee, v242
	v_exp_f32_e32 v68, v68
	v_exp_f32_e32 v69, v69
	v_exp_f32_e32 v70, v70
	v_exp_f32_e32 v71, v71
	v_exp_f32_e32 v72, v72
	v_exp_f32_e32 v73, v73
	v_exp_f32_e32 v74, v74
	v_exp_f32_e32 v75, v75
	v_exp_f32_e32 v76, v76
	v_exp_f32_e32 v77, v77
	v_exp_f32_e32 v78, v78
	v_exp_f32_e32 v79, v79
	v_exp_f32_e32 v80, v80
	v_exp_f32_e32 v81, v81
	v_exp_f32_e32 v82, v82
	v_exp_f32_e32 v83, v83
	v_cvt_pk_bf16_f32 v168, v68, v69
	v_cvt_pk_bf16_f32 v169, v70, v71
	v_cvt_pk_bf16_f32 v170, v72, v73
	v_cvt_pk_bf16_f32 v171, v74, v75
	v_cvt_pk_bf16_f32 v172, v76, v77
	v_cvt_pk_bf16_f32 v173, v78, v79
	v_cvt_pk_bf16_f32 v174, v80, v81
	v_cvt_pk_bf16_f32 v175, v82, v83
	s_waitcnt lgkmcnt(0)
	s_nop 0
	v_permlane32_swap_b32_e32 v168, v170
	v_permlane32_swap_b32_e32 v169, v171
	v_permlane32_swap_b32_e32 v172, v174
	v_permlane32_swap_b32_e32 v173, v175
	s_nop 1
	s_setprio 1
	v_mfma_f32_32x32x16_bf16 v[52:67], v[168:171], v[84:87], v[52:67]
	ds_read_b64_tr_b16 v[84:85], v248 offset:8192
	ds_read_b64_tr_b16 v[86:87], v248 offset:10240
	v_fmamk_f32 v210, v210, 0x3e0293ee, v249
	v_fmamk_f32 v211, v211, 0x3e0293ee, v249
	v_fmamk_f32 v212, v212, 0x3e0293ee, v249
	v_fmamk_f32 v213, v213, 0x3e0293ee, v249
	v_fmamk_f32 v214, v214, 0x3e0293ee, v249
	v_fmamk_f32 v215, v215, 0x3e0293ee, v249
	v_fmamk_f32 v216, v216, 0x3e0293ee, v249
	v_fmamk_f32 v217, v217, 0x3e0293ee, v249
	v_fmamk_f32 v218, v218, 0x3e0293ee, v249
	v_fmamk_f32 v219, v219, 0x3e0293ee, v249
	v_mfma_f32_32x32x16_bf16 v[36:51], v[168:171], v[92:95], v[36:51]
	ds_read_b64_tr_b16 v[92:93], v248 offset:8704
	ds_read_b64_tr_b16 v[94:95], v248 offset:10752
	v_fmamk_f32 v220, v220, 0x3e0293ee, v249
	v_fmamk_f32 v221, v221, 0x3e0293ee, v249
	v_fmamk_f32 v222, v222, 0x3e0293ee, v249
	v_fmamk_f32 v223, v223, 0x3e0293ee, v249
	v_fmamk_f32 v224, v224, 0x3e0293ee, v249
	v_fmamk_f32 v225, v225, 0x3e0293ee, v249
	v_exp_f32_e32 v210, v210
	v_add_f32_e32 v246, v68, v69
	v_exp_f32_e32 v211, v211
	v_add_f32_e32 v247, v70, v71
	v_mfma_f32_32x32x16_bf16 v[20:35], v[168:171], v[194:197], v[20:35]
	ds_read_b64_tr_b16 v[194:195], v248 offset:9216
	ds_read_b64_tr_b16 v[196:197], v248 offset:11264
	v_exp_f32_e32 v212, v212
	v_add_f32_e32 v246, v246, v72
	v_exp_f32_e32 v213, v213
	v_add_f32_e32 v246, v246, v73
	v_exp_f32_e32 v214, v214
	v_add_f32_e32 v247, v247, v74
	v_exp_f32_e32 v215, v215
	v_add_f32_e32 v247, v247, v75
	v_exp_f32_e32 v216, v216
	v_add_f32_e32 v246, v246, v76
	v_mfma_f32_32x32x16_bf16 v[4:19], v[168:171], v[202:205], v[4:19]
	ds_read_b64_tr_b16 v[202:203], v248 offset:9728
	ds_read_b64_tr_b16 v[204:205], v248 offset:11776
	v_exp_f32_e32 v217, v217
	v_add_f32_e32 v246, v246, v77
	v_exp_f32_e32 v218, v218
	v_add_f32_e32 v247, v247, v78
	v_exp_f32_e32 v219, v219
	v_add_f32_e32 v247, v247, v79
	v_exp_f32_e32 v220, v220
	v_add_f32_e32 v246, v246, v80
	v_exp_f32_e32 v221, v221
	v_add_f32_e32 v246, v246, v81
	v_mfma_f32_32x32x16_bf16 v[52:67], v[172:175], v[88:91], v[52:67]
	ds_read_b64_tr_b16 v[88:89], v248 offset:12288
	ds_read_b64_tr_b16 v[90:91], v248 offset:14336
	v_exp_f32_e32 v222, v222
	v_add_f32_e32 v247, v247, v82
	v_exp_f32_e32 v223, v223
	v_add_f32_e32 v247, v247, v83
	v_exp_f32_e32 v224, v224
	v_exp_f32_e32 v225, v225
	v_add_f32_e32 v246, v246, v210
	v_add_f32_e32 v246, v246, v211
	v_add_f32_e32 v247, v247, v212
	v_add_f32_e32 v247, v247, v213
	v_mfma_f32_32x32x16_bf16 v[36:51], v[172:175], v[96:99], v[36:51]
	ds_read_b64_tr_b16 v[96:97], v248 offset:12800
	ds_read_b64_tr_b16 v[98:99], v248 offset:14848
	v_add_f32_e32 v246, v246, v214
	v_add_f32_e32 v246, v246, v215
	v_add_f32_e32 v247, v247, v216
	v_add_f32_e32 v247, v247, v217
	v_add_f32_e32 v246, v246, v218
	v_add_f32_e32 v246, v246, v219
	v_add_f32_e32 v247, v247, v220
	v_add_f32_e32 v247, v247, v221
	v_add_f32_e32 v246, v246, v222
	v_add_f32_e32 v246, v246, v223
	v_mfma_f32_32x32x16_bf16 v[20:35], v[172:175], v[198:201], v[20:35]
	ds_read_b64_tr_b16 v[198:199], v248 offset:13312
	ds_read_b64_tr_b16 v[200:201], v248 offset:15360
	v_add_f32_e32 v247, v247, v224
	v_add_f32_e32 v247, v247, v225
	v_add_f32_e32 v246, v246, v247
	v_add_f32_e32 v162, v162, v246
	v_cvt_pk_bf16_f32 v68, v210, v211
	v_cvt_pk_bf16_f32 v69, v212, v213
	v_cvt_pk_bf16_f32 v70, v214, v215
	v_cvt_pk_bf16_f32 v71, v216, v217
	v_cvt_pk_bf16_f32 v72, v218, v219
	v_cvt_pk_bf16_f32 v73, v220, v221
	v_mfma_f32_32x32x16_bf16 v[4:19], v[172:175], v[206:209], v[4:19]
	ds_read_b64_tr_b16 v[206:207], v248 offset:13824
	ds_read_b64_tr_b16 v[208:209], v248 offset:15872
	v_cvt_pk_bf16_f32 v74, v222, v223
	v_cvt_pk_bf16_f32 v75, v224, v225
	v_permlane32_swap_b32_e32 v68, v70
	v_permlane32_swap_b32_e32 v69, v71
	v_permlane32_swap_b32_e32 v72, v74
	v_permlane32_swap_b32_e32 v73, v75
	s_nop 1
	s_waitcnt lgkmcnt(14)
	v_mfma_f32_32x32x16_bf16 v[52:67], v[68:71], v[84:87], v[52:67]
	s_waitcnt lgkmcnt(12)
	v_mfma_f32_32x32x16_bf16 v[36:51], v[68:71], v[92:95], v[36:51]
	s_waitcnt lgkmcnt(10)
	v_mfma_f32_32x32x16_bf16 v[20:35], v[68:71], v[194:197], v[20:35]
	s_waitcnt lgkmcnt(8)
	v_mfma_f32_32x32x16_bf16 v[4:19], v[68:71], v[202:205], v[4:19]
	s_waitcnt lgkmcnt(6)
	v_mfma_f32_32x32x16_bf16 v[52:67], v[72:75], v[88:91], v[52:67]
	s_waitcnt lgkmcnt(4)
	v_mfma_f32_32x32x16_bf16 v[36:51], v[72:75], v[96:99], v[36:51]
	s_waitcnt lgkmcnt(2)
	v_mfma_f32_32x32x16_bf16 v[20:35], v[72:75], v[198:201], v[20:35]
	s_waitcnt lgkmcnt(0)
	v_mfma_f32_32x32x16_bf16 v[4:19], v[72:75], v[206:209], v[4:19]
	s_setprio 0
	s_add_i32 s26, s26, -1
	s_add_i32 s61, s61, 1
	s_addk_i32 s97, 0x4000
	s_cmp_eq_u32 s26, 0
	s_cbranch_scc1 .LBB0_335
	s_branch .LBB0_316

; #define KSWZ(row, colB) ((row) * 256 + ((colB) ^ (KSWZF(row) << 4)))
; #define SBAR() __builtin_amdgcn_sched_barrier(0)
; template <int H> __device__ __forceinline__ void qkt_half(f32x16& pz, const char* Ks, const bf16x8* qr, int r32, int hi) {
;   bf16x8 kf[8];
; #pragma unroll
;   for (int d0 = 0; d0 < 8; ++d0) { const int cb = (d0 * 16 + hi * 8) * 2; kf[d0] = *reinterpret_cast<const bf16x8*>(Ks + KSWZ(32 * H + r32, cb)); }
;   asm volatile("s_waitcnt lgkmcnt(0)" ::: "memory"); SBAR();
;   f32x16 pb = {};
; #pragma unroll
;   for (int d0 = 0; d0 < 8; d0 += 2) {
;     pz = __builtin_amdgcn_mfma_f32_32x32x16_bf16(kf[d0], qr[d0], pz, 0, 0, 0);
;     pb = __builtin_amdgcn_mfma_f32_32x32x16_bf16(kf[d0 + 1], qr[d0 + 1], pb, 0, 0, 0); }
; #pragma unroll
;   for (int r = 0; r < 16; ++r) pz[r] += pb[r];
; }
; template <int MODE>
; __device__ __forceinline__ void nsa_single(const Params& p, const LaneId& L, int q0, int g, int ntiles, int first, char* smem, const bf16x8* qr, float gate, f32x16* o) {
;     ...
;     int pb = row, lo, hl; float badd = 0.f;
;     if (MODE == 1) { const int j = row >> 6; lo = NEG; const bool fl = ((mysel[j >> 5] >> (j & 31)) & 1u) != 0u;
;       if (row == q0) hl = fl ? (L.tq - pb) : NEG; else { hl = 1000; badd = fl ? 0.f : -INFINITY; } }
;     else { lo = L.tq - 512 - pb; hl = L.tq - pb; }
;     constexpr float C = 0.08838834764831845f * LOG2E;
;     const float A1 = L.sl2; const float B1 = L.sl2 * (float)(pb - L.tq) + A1 * (float)(4 * L.hi) + badd;
;     const int lo2 = lo - 4 * L.hi, hl2 = hl - 4 * L.hi;
;     const bool nomask = __all(lo2 < 0 && hl2 >= 63);
.LBB0_344:
	v_add_u32_e32 v163, 0xfffffe00, v161
	v_cmp_lt_i32_e32 vcc, 62, v161
	v_cmp_gt_i32_e64 s[12:13], 0, v163
	v_cvt_f32_i32_e32 v2, v162
	s_nop 3
	s_and_b64 vcc, s[12:13], vcc
	s_cmp_lg_u64 vcc, exec
	s_cselect_b64 s[98:99], -1, 0
	v_fma_f32 v2, v132, v2, v150
	v_add_f32_e32 v243, 0x41000000, v165
	v_mov_b32_e32 v250, v2
	s_setprio 1
	s_waitcnt lgkmcnt(7)
	v_mfma_f32_32x32x16_bf16 v[68:83], v[84:87], v[100:103], v[226:241]
	v_add_u32_e32 v249, v242, v152
	ds_read_b128 v[84:87], v249 offset:8192
	s_waitcnt lgkmcnt(7)
	v_mfma_f32_32x32x16_bf16 v[68:83], v[88:91], v[104:107], v[68:83]
	v_add_u32_e32 v251, v242, v153
	ds_read_b128 v[88:91], v251 offset:8192
	s_waitcnt lgkmcnt(7)
	v_mfma_f32_32x32x16_bf16 v[68:83], v[92:95], v[108:111], v[68:83]
	v_add_u32_e32 v249, v242, v154
	ds_read_b128 v[92:95], v249 offset:8192
	s_waitcnt lgkmcnt(7)
	v_mfma_f32_32x32x16_bf16 v[68:83], v[96:99], v[112:115], v[68:83]
	v_add_u32_e32 v251, v242, v155
	ds_read_b128 v[96:99], v251 offset:8192
	s_waitcnt lgkmcnt(7)
	v_mfma_f32_32x32x16_bf16 v[68:83], v[194:197], v[116:119], v[68:83]
	v_add_u32_e32 v249, v242, v156
	ds_read_b128 v[194:197], v249 offset:8192
	s_waitcnt lgkmcnt(7)
	v_mfma_f32_32x32x16_bf16 v[68:83], v[198:201], v[120:123], v[68:83]
	v_add_u32_e32 v251, v242, v157
	ds_read_b128 v[198:201], v251 offset:8192
	s_waitcnt lgkmcnt(7)
	v_mfma_f32_32x32x16_bf16 v[68:83], v[202:205], v[124:127], v[68:83]
	v_add_u32_e32 v249, v242, v158
	ds_read_b128 v[202:205], v249 offset:8192
	s_waitcnt lgkmcnt(7)
	v_mfma_f32_32x32x16_bf16 v[68:83], v[206:209], v[128:131], v[68:83]
	v_add_u32_e32 v251, v242, v159
	ds_read_b128 v[206:209], v251 offset:8192
	s_waitcnt lgkmcnt(7)
	v_mfma_f32_32x32x16_bf16 v[210:225], v[84:87], v[100:103], v[226:241]
	ds_read_b64_tr_b16 v[84:85], v248 offset:0
	ds_read_b64_tr_b16 v[86:87], v248 offset:2048
	s_waitcnt lgkmcnt(8)
	v_mfma_f32_32x32x16_bf16 v[210:225], v[88:91], v[104:107], v[210:225]
	ds_read_b64_tr_b16 v[88:89], v248 offset:4096
	ds_read_b64_tr_b16 v[90:91], v248 offset:6144
	s_waitcnt lgkmcnt(9)
	v_mfma_f32_32x32x16_bf16 v[210:225], v[92:95], v[108:111], v[210:225]
	ds_read_b64_tr_b16 v[92:93], v248 offset:512
	ds_read_b64_tr_b16 v[94:95], v248 offset:2560
	s_waitcnt lgkmcnt(10)
	v_mfma_f32_32x32x16_bf16 v[210:225], v[96:99], v[112:115], v[210:225]
	ds_read_b64_tr_b16 v[96:97], v248 offset:4608
	ds_read_b64_tr_b16 v[98:99], v248 offset:6656
	s_waitcnt lgkmcnt(11)
	v_mfma_f32_32x32x16_bf16 v[210:225], v[194:197], v[116:119], v[210:225]
	ds_read_b64_tr_b16 v[194:195], v248 offset:1024
	ds_read_b64_tr_b16 v[196:197], v248 offset:3072
	s_waitcnt lgkmcnt(12)
	v_mfma_f32_32x32x16_bf16 v[210:225], v[198:201], v[120:123], v[210:225]
	ds_read_b64_tr_b16 v[198:199], v248 offset:5120
	ds_read_b64_tr_b16 v[200:201], v248 offset:7168
	s_waitcnt lgkmcnt(13)
	v_mfma_f32_32x32x16_bf16 v[210:225], v[202:205], v[124:127], v[210:225]
	ds_read_b64_tr_b16 v[202:203], v248 offset:1536
	ds_read_b64_tr_b16 v[204:205], v248 offset:3584
	s_waitcnt lgkmcnt(14)
	v_mfma_f32_32x32x16_bf16 v[210:225], v[206:209], v[128:131], v[210:225]
	ds_read_b64_tr_b16 v[206:207], v248 offset:5632
	ds_read_b64_tr_b16 v[208:209], v248 offset:7680
	s_setprio 0
	v_fmamk_f32 v251, v132, 0x42000000, v2
	s_and_b64 vcc, exec, s[98:99]
	s_cbranch_vccz .Lwin_nm
; template <bool MASK, int H> __device__ __forceinline__ void bias_half(f32x16& pz, float C, float A1, float B1, int lo, int hl) {
; #pragma unroll
;   for (int r = 0; r < 16; ++r) {
;     const int c0 = (r & 3) + 8 * (r >> 2) + 32 * H;
;     float s0 = fmaf(pz[r], C, fmaf(A1, (float)c0, B1));
;     if (MASK) s0 = (c0 > lo && c0 <= hl) ? s0 : -INFINITY;
;     pz[r] = s0;
;   }
; }
; template <int MODE>
; __device__ __forceinline__ void nsa_single(const Params& p, const LaneId& L, int q0, int g, int ntiles, int first, char* smem, const bf16x8* qr, float gate, f32x16* o) {
;     ...
;     else { lo = L.tq - 512 - pb; hl = L.tq - pb; }
	v_cmp_lt_i32_e32 vcc, -1, v161
	v_cmp_lt_i32_e64 s[10:11], 0, v161
	v_cmp_lt_i32_e64 s[12:13], 1, v161
	v_cmp_lt_i32_e64 s[2:3], 2, v161
	s_nop 0
	v_cndmask_b32_e32 v68, v183, v68, vcc
	v_cndmask_b32_e64 v69, v183, v69, s[10:11]
	v_cndmask_b32_e64 v70, v183, v70, s[12:13]
	v_cndmask_b32_e64 v71, v183, v71, s[2:3]
	v_cmp_lt_i32_e32 vcc, 7, v161
	v_cmp_lt_i32_e64 s[10:11], 8, v161
	v_cmp_lt_i32_e64 s[12:13], 9, v161
	v_cmp_lt_i32_e64 s[2:3], 10, v161
	s_nop 0
	v_cndmask_b32_e32 v72, v183, v72, vcc
	v_cndmask_b32_e64 v73, v183, v73, s[10:11]
	v_cndmask_b32_e64 v74, v183, v74, s[12:13]
	v_cndmask_b32_e64 v75, v183, v75, s[2:3]
	v_cmp_lt_i32_e32 vcc, 15, v161
	v_cmp_lt_i32_e64 s[10:11], 16, v161
	v_cmp_lt_i32_e64 s[12:13], 17, v161
	v_cmp_lt_i32_e64 s[2:3], 18, v161
	s_nop 0
	v_cndmask_b32_e32 v76, v183, v76, vcc
	v_cndmask_b32_e64 v77, v183, v77, s[10:11]
	v_cndmask_b32_e64 v78, v183, v78, s[12:13]
	v_cndmask_b32_e64 v79, v183, v79, s[2:3]
	v_cmp_lt_i32_e32 vcc, 23, v161
	v_cmp_lt_i32_e64 s[10:11], 24, v161
	v_cmp_lt_i32_e64 s[12:13], 25, v161
	v_cmp_lt_i32_e64 s[2:3], 26, v161
	s_nop 0
	v_cndmask_b32_e32 v80, v183, v80, vcc
	v_cndmask_b32_e64 v81, v183, v81, s[10:11]
	v_cndmask_b32_e64 v82, v183, v82, s[12:13]
	v_cndmask_b32_e64 v83, v183, v83, s[2:3]
	v_cmp_gt_i32_e32 vcc, 0, v163
	v_cmp_gt_i32_e64 s[10:11], 1, v163
	v_cmp_gt_i32_e64 s[12:13], 2, v163
	v_cmp_gt_i32_e64 s[2:3], 3, v163
	s_nop 0
	v_cndmask_b32_e32 v68, v183, v68, vcc
	v_cndmask_b32_e64 v69, v183, v69, s[10:11]
	v_cndmask_b32_e64 v70, v183, v70, s[12:13]
	v_cndmask_b32_e64 v71, v183, v71, s[2:3]
	v_cmp_gt_i32_e32 vcc, 8, v163
	v_cmp_gt_i32_e64 s[10:11], 9, v163
	v_cmp_gt_i32_e64 s[12:13], 10, v163
	v_cmp_gt_i32_e64 s[2:3], 11, v163
	s_nop 0
	v_cndmask_b32_e32 v72, v183, v72, vcc
	v_cndmask_b32_e64 v73, v183, v73, s[10:11]
	v_cndmask_b32_e64 v74, v183, v74, s[12:13]
	v_cndmask_b32_e64 v75, v183, v75, s[2:3]
	v_cmp_gt_i32_e32 vcc, 16, v163
	v_cmp_gt_i32_e64 s[10:11], 17, v163
	v_cmp_gt_i32_e64 s[12:13], 18, v163
	v_cmp_gt_i32_e64 s[2:3], 19, v163
	s_nop 0
	v_cndmask_b32_e32 v76, v183, v76, vcc
	v_cndmask_b32_e64 v77, v183, v77, s[10:11]
	v_cndmask_b32_e64 v78, v183, v78, s[12:13]
	v_cndmask_b32_e64 v79, v183, v79, s[2:3]
	v_cmp_gt_i32_e32 vcc, 24, v163
	v_cmp_gt_i32_e64 s[10:11], 25, v163
	v_cmp_gt_i32_e64 s[12:13], 26, v163
	v_cmp_gt_i32_e64 s[2:3], 27, v163
	s_nop 0
	v_cndmask_b32_e32 v80, v183, v80, vcc
	v_cndmask_b32_e64 v81, v183, v81, s[10:11]
	v_cndmask_b32_e64 v82, v183, v82, s[12:13]
	v_cndmask_b32_e64 v83, v183, v83, s[2:3]
	v_cmp_lt_i32_e32 vcc, 31, v161
	v_cmp_lt_i32_e64 s[10:11], 32, v161
	v_cmp_lt_i32_e64 s[12:13], 33, v161
	v_cmp_lt_i32_e64 s[2:3], 34, v161
	s_nop 0
	v_cndmask_b32_e32 v210, v183, v210, vcc
	v_cndmask_b32_e64 v211, v183, v211, s[10:11]
	v_cndmask_b32_e64 v212, v183, v212, s[12:13]
	v_cndmask_b32_e64 v213, v183, v213, s[2:3]
	v_cmp_lt_i32_e32 vcc, 39, v161
	v_cmp_lt_i32_e64 s[10:11], 40, v161
	v_cmp_lt_i32_e64 s[12:13], 41, v161
	v_cmp_lt_i32_e64 s[2:3], 42, v161
	s_nop 0
	v_cndmask_b32_e32 v214, v183, v214, vcc
	v_cndmask_b32_e64 v215, v183, v215, s[10:11]
	v_cndmask_b32_e64 v216, v183, v216, s[12:13]
	v_cndmask_b32_e64 v217, v183, v217, s[2:3]
	v_cmp_lt_i32_e32 vcc, 47, v161
	v_cmp_lt_i32_e64 s[10:11], 48, v161
	v_cmp_lt_i32_e64 s[12:13], 49, v161
	v_cmp_lt_i32_e64 s[2:3], 50, v161
	s_nop 0
	v_cndmask_b32_e32 v218, v183, v218, vcc
	v_cndmask_b32_e64 v219, v183, v219, s[10:11]
	v_cndmask_b32_e64 v220, v183, v220, s[12:13]
	v_cndmask_b32_e64 v221, v183, v221, s[2:3]
	v_cmp_lt_i32_e32 vcc, 55, v161
	v_cmp_lt_i32_e64 s[10:11], 56, v161
	v_cmp_lt_i32_e64 s[12:13], 57, v161
	v_cmp_lt_i32_e64 s[2:3], 58, v161
	s_nop 0
	v_cndmask_b32_e32 v222, v183, v222, vcc
	v_cndmask_b32_e64 v223, v183, v223, s[10:11]
	v_cndmask_b32_e64 v224, v183, v224, s[12:13]
	v_cndmask_b32_e64 v225, v183, v225, s[2:3]
	v_cmp_gt_i32_e32 vcc, 32, v163
	v_cmp_gt_i32_e64 s[10:11], 33, v163
	v_cmp_gt_i32_e64 s[12:13], 34, v163
	v_cmp_gt_i32_e64 s[2:3], 35, v163
	s_nop 0
	v_cndmask_b32_e32 v210, v183, v210, vcc
	v_cndmask_b32_e64 v211, v183, v211, s[10:11]
	v_cndmask_b32_e64 v212, v183, v212, s[12:13]
	v_cndmask_b32_e64 v213, v183, v213, s[2:3]
	v_cmp_gt_i32_e32 vcc, 40, v163
	v_cmp_gt_i32_e64 s[10:11], 41, v163
	v_cmp_gt_i32_e64 s[12:13], 42, v163
	v_cmp_gt_i32_e64 s[2:3], 43, v163
	s_nop 0
	v_cndmask_b32_e32 v214, v183, v214, vcc
	v_cndmask_b32_e64 v215, v183, v215, s[10:11]
	v_cndmask_b32_e64 v216, v183, v216, s[12:13]
	v_cndmask_b32_e64 v217, v183, v217, s[2:3]
	v_cmp_gt_i32_e32 vcc, 48, v163
	v_cmp_gt_i32_e64 s[10:11], 49, v163
	v_cmp_gt_i32_e64 s[12:13], 50, v163
	v_cmp_gt_i32_e64 s[2:3], 51, v163
	s_nop 0
	v_cndmask_b32_e32 v218, v183, v218, vcc
	v_cndmask_b32_e64 v219, v183, v219, s[10:11]
	v_cndmask_b32_e64 v220, v183, v220, s[12:13]
	v_cndmask_b32_e64 v221, v183, v221, s[2:3]
	v_cmp_gt_i32_e32 vcc, 56, v163
	v_cmp_gt_i32_e64 s[10:11], 57, v163
	v_cmp_gt_i32_e64 s[12:13], 58, v163
	v_cmp_gt_i32_e64 s[2:3], 59, v163
	s_nop 0
	v_cndmask_b32_e32 v222, v183, v222, vcc
	v_cndmask_b32_e64 v223, v183, v223, s[10:11]
	v_cndmask_b32_e64 v224, v183, v224, s[12:13]
	v_cndmask_b32_e64 v225, v183, v225, s[2:3]

; #define SBAR() __builtin_amdgcn_sched_barrier(0)
; #define TRQ(D0) const s16x4 l0_##D0 = tr_read<v_rd_off(D0, 2 * H, 0)>(vb), h0_##D0 = tr_read<v_rd_off(D0, 2 * H, 1)>(vb), \
;                             l1_##D0 = tr_read<v_rd_off(D0, 2 * H + 1, 0)>(vb), h1_##D0 = tr_read<v_rd_off(D0, 2 * H + 1, 1)>(vb)
; template <int H> __device__ __forceinline__ void pv_half(f32x16* o, int vb, bf16x8 paA, bf16x8 paB) {
;     ...
;   TRQ(0); TRQ(1); TRQ(2); TRQ(3);
;     ...
;   asm volatile("s_waitcnt lgkmcnt(0)" ::: "memory"); SBAR();
;     ...
;   o[0] = __builtin_amdgcn_mfma_f32_32x32x16_bf16(paA, PK(l0_0, h0_0), o[0], 0, 0, 0);
;   o[1] = __builtin_amdgcn_mfma_f32_32x32x16_bf16(paA, PK(l0_1, h0_1), o[1], 0, 0, 0);
;   o[2] = __builtin_amdgcn_mfma_f32_32x32x16_bf16(paA, PK(l0_2, h0_2), o[2], 0, 0, 0);
;   o[3] = __builtin_amdgcn_mfma_f32_32x32x16_bf16(paA, PK(l0_3, h0_3), o[3], 0, 0, 0);
;   o[0] = __builtin_amdgcn_mfma_f32_32x32x16_bf16(paB, PK(l1_0, h1_0), o[0], 0, 0, 0);
;   o[1] = __builtin_amdgcn_mfma_f32_32x32x16_bf16(paB, PK(l1_1, h1_1), o[1], 0, 0, 0);
;   o[2] = __builtin_amdgcn_mfma_f32_32x32x16_bf16(paB, PK(l1_2, h1_2), o[2], 0, 0, 0);
;   o[3] = __builtin_amdgcn_mfma_f32_32x32x16_bf16(paB, PK(l1_3, h1_3), o[3], 0, 0, 0);
;     ...
; }
.Lwin_nr:
	v_sub_f32_e32 v242, v250, v165
	v_sub_f32_e32 v249, v251, v165
	s_nop 0
	v_fmamk_f32 v68, v68, 0x3e0293ee, v242
	v_fmamk_f32 v69, v69, 0x3e0293ee, v242
	v_fmamk_f32 v70, v70, 0x3e0293ee, v242
	v_fmamk_f32 v71, v71, 0x3e0293ee, v242
	v_fmamk_f32 v72, v72, 0x3e0293ee, v242
	v_fmamk_f32 v73, v73, 0x3e0293ee, v242
	v_fmamk_f32 v74, v74, 0x3e0293ee, v242
	v_fmamk_f32 v75, v75, 0x3e0293ee, v242
	v_fmamk_f32 v76, v76, 0x3e0293ee, v242
	v_fmamk_f32 v77, v77, 0x3e0293ee, v242
	v_fmamk_f32 v78, v78, 0x3e0293ee, v242
	v_fmamk_f32 v79, v79, 0x3e0293ee, v242
	v_fmamk_f32 v80, v80, 0x3e0293ee, v242
	v_fmamk_f32 v81, v81, 0x3e0293ee, v242
	v_fmamk_f32 v82, v82, 0x3e0293ee, v242
	v_fmamk_f32 v83, v83, 0x3e0293ee, v242
	v_exp_f32_e32 v68, v68
	v_exp_f32_e32 v69, v69
	v_exp_f32_e32 v70, v70
	v_exp_f32_e32 v71, v71
	v_exp_f32_e32 v72, v72
	v_exp_f32_e32 v73, v73
	v_exp_f32_e32 v74, v74
	v_exp_f32_e32 v75, v75
	v_exp_f32_e32 v76, v76
	v_exp_f32_e32 v77, v77
	v_exp_f32_e32 v78, v78
	v_exp_f32_e32 v79, v79
	v_exp_f32_e32 v80, v80
	v_exp_f32_e32 v81, v81
	v_exp_f32_e32 v82, v82
	v_exp_f32_e32 v83, v83
	v_cvt_pk_bf16_f32 v168, v68, v69
	v_cvt_pk_bf16_f32 v169, v70, v71
	v_cvt_pk_bf16_f32 v170, v72, v73
	v_cvt_pk_bf16_f32 v171, v74, v75
	v_cvt_pk_bf16_f32 v172, v76, v77
	v_cvt_pk_bf16_f32 v173, v78, v79
	v_cvt_pk_bf16_f32 v174, v80, v81
	v_cvt_pk_bf16_f32 v175, v82, v83
	s_waitcnt lgkmcnt(0)
	s_nop 0
	v_permlane32_swap_b32_e32 v168, v170
	v_permlane32_swap_b32_e32 v169, v171
	v_permlane32_swap_b32_e32 v172, v174
	v_permlane32_swap_b32_e32 v173, v175
	s_nop 1
	s_setprio 1
	v_mfma_f32_32x32x16_bf16 v[52:67], v[168:171], v[84:87], v[52:67]
	ds_read_b64_tr_b16 v[84:85], v248 offset:8192
	ds_read_b64_tr_b16 v[86:87], v248 offset:10240
	v_fmamk_f32 v210, v210, 0x3e0293ee, v249
	v_fmamk_f32 v211, v211, 0x3e0293ee, v249
	v_fmamk_f32 v212, v212, 0x3e0293ee, v249
	v_fmamk_f32 v213, v213, 0x3e0293ee, v249
	v_fmamk_f32 v214, v214, 0x3e0293ee, v249
	v_fmamk_f32 v215, v215, 0x3e0293ee, v249
	v_fmamk_f32 v216, v216, 0x3e0293ee, v249
	v_fmamk_f32 v217, v217, 0x3e0293ee, v249
	v_fmamk_f32 v218, v218, 0x3e0293ee, v249
	v_fmamk_f32 v219, v219, 0x3e0293ee, v249
	v_mfma_f32_32x32x16_bf16 v[36:51], v[168:171], v[92:95], v[36:51]
	ds_read_b64_tr_b16 v[92:93], v248 offset:8704
	ds_read_b64_tr_b16 v[94:95], v248 offset:10752
	v_fmamk_f32 v220, v220, 0x3e0293ee, v249
	v_fmamk_f32 v221, v221, 0x3e0293ee, v249
	v_fmamk_f32 v222, v222, 0x3e0293ee, v249
	v_fmamk_f32 v223, v223, 0x3e0293ee, v249
	v_fmamk_f32 v224, v224, 0x3e0293ee, v249
	v_fmamk_f32 v225, v225, 0x3e0293ee, v249
	v_exp_f32_e32 v210, v210
	v_add_f32_e32 v246, v68, v69
	v_exp_f32_e32 v211, v211
	v_add_f32_e32 v247, v70, v71
	v_mfma_f32_32x32x16_bf16 v[20:35], v[168:171], v[194:197], v[20:35]
	ds_read_b64_tr_b16 v[194:195], v248 offset:9216
	ds_read_b64_tr_b16 v[196:197], v248 offset:11264
	v_exp_f32_e32 v212, v212
	v_add_f32_e32 v246, v246, v72
	v_exp_f32_e32 v213, v213
	v_add_f32_e32 v246, v246, v73
	v_exp_f32_e32 v214, v214
	v_add_f32_e32 v247, v247, v74
	v_exp_f32_e32 v215, v215
	v_add_f32_e32 v247, v247, v75
	v_exp_f32_e32 v216, v216
	v_add_f32_e32 v246, v246, v76
	v_mfma_f32_32x32x16_bf16 v[4:19], v[168:171], v[202:205], v[4:19]
	ds_read_b64_tr_b16 v[202:203], v248 offset:9728
	ds_read_b64_tr_b16 v[204:205], v248 offset:11776
	v_exp_f32_e32 v217, v217
	v_add_f32_e32 v246, v246, v77
	v_exp_f32_e32 v218, v218
	v_add_f32_e32 v247, v247, v78
	v_exp_f32_e32 v219, v219
	v_add_f32_e32 v247, v247, v79
	v_exp_f32_e32 v220, v220
	v_add_f32_e32 v246, v246, v80
	v_exp_f32_e32 v221, v221
	v_add_f32_e32 v246, v246, v81
	v_mfma_f32_32x32x16_bf16 v[52:67], v[172:175], v[88:91], v[52:67]
	ds_read_b64_tr_b16 v[88:89], v248 offset:12288
	ds_read_b64_tr_b16 v[90:91], v248 offset:14336
	v_exp_f32_e32 v222, v222
	v_add_f32_e32 v247, v247, v82
	v_exp_f32_e32 v223, v223
	v_add_f32_e32 v247, v247, v83
	v_exp_f32_e32 v224, v224
	v_exp_f32_e32 v225, v225
	v_add_f32_e32 v246, v246, v210
	v_add_f32_e32 v246, v246, v211
	v_add_f32_e32 v247, v247, v212
	v_add_f32_e32 v247, v247, v213
	v_mfma_f32_32x32x16_bf16 v[36:51], v[172:175], v[96:99], v[36:51]
	ds_read_b64_tr_b16 v[96:97], v248 offset:12800
	ds_read_b64_tr_b16 v[98:99], v248 offset:14848
	v_add_f32_e32 v246, v246, v214
	v_add_f32_e32 v246, v246, v215
	v_add_f32_e32 v247, v247, v216
	v_add_f32_e32 v247, v247, v217
	v_add_f32_e32 v246, v246, v218
	v_add_f32_e32 v246, v246, v219
	v_add_f32_e32 v247, v247, v220
	v_add_f32_e32 v247, v247, v221
	v_add_f32_e32 v246, v246, v222
	v_add_f32_e32 v246, v246, v223
	v_mfma_f32_32x32x16_bf16 v[20:35], v[172:175], v[198:201], v[20:35]
	ds_read_b64_tr_b16 v[198:199], v248 offset:13312
	ds_read_b64_tr_b16 v[200:201], v248 offset:15360
	v_add_f32_e32 v247, v247, v224
	v_add_f32_e32 v247, v247, v225
	v_add_f32_e32 v246, v246, v247
	v_add_f32_e32 v143, v143, v246
	v_cvt_pk_bf16_f32 v68, v210, v211
	v_cvt_pk_bf16_f32 v69, v212, v213
	v_cvt_pk_bf16_f32 v70, v214, v215
	v_cvt_pk_bf16_f32 v71, v216, v217
	v_cvt_pk_bf16_f32 v72, v218, v219
	v_cvt_pk_bf16_f32 v73, v220, v221
	v_mfma_f32_32x32x16_bf16 v[4:19], v[172:175], v[206:209], v[4:19]
	ds_read_b64_tr_b16 v[206:207], v248 offset:13824
	ds_read_b64_tr_b16 v[208:209], v248 offset:15872
	v_cvt_pk_bf16_f32 v74, v222, v223
	v_cvt_pk_bf16_f32 v75, v224, v225
	v_permlane32_swap_b32_e32 v68, v70
	v_permlane32_swap_b32_e32 v69, v71
	v_permlane32_swap_b32_e32 v72, v74
	v_permlane32_swap_b32_e32 v73, v75
	s_nop 1
	s_waitcnt lgkmcnt(14)
	v_mfma_f32_32x32x16_bf16 v[52:67], v[68:71], v[84:87], v[52:67]
	s_waitcnt lgkmcnt(12)
	v_mfma_f32_32x32x16_bf16 v[36:51], v[68:71], v[92:95], v[36:51]
	s_waitcnt lgkmcnt(10)
	v_mfma_f32_32x32x16_bf16 v[20:35], v[68:71], v[194:197], v[20:35]
	s_waitcnt lgkmcnt(8)
	v_mfma_f32_32x32x16_bf16 v[4:19], v[68:71], v[202:205], v[4:19]
	s_waitcnt lgkmcnt(6)
	v_mfma_f32_32x32x16_bf16 v[52:67], v[72:75], v[88:91], v[52:67]
	s_waitcnt lgkmcnt(4)
	v_mfma_f32_32x32x16_bf16 v[36:51], v[72:75], v[96:99], v[36:51]
	s_waitcnt lgkmcnt(2)
	v_mfma_f32_32x32x16_bf16 v[20:35], v[72:75], v[198:201], v[20:35]
	s_waitcnt lgkmcnt(0)
	v_mfma_f32_32x32x16_bf16 v[4:19], v[72:75], v[206:209], v[4:19]
	s_setprio 0
	s_addk_i32 s1, 0x4000
	s_add_i32 s0, s0, 1
	v_lshl_add_u64 v[134:135], v[134:135], 0, s[20:21]
	v_lshl_add_u64 v[136:137], v[136:137], 0, s[20:21]
	v_lshl_add_u64 v[138:139], v[138:139], 0, s[20:21]
	v_lshl_add_u64 v[140:141], v[140:141], 0, s[20:21]
	v_add_u32_e32 v161, 64, v161
	v_subrev_u32_e32 v162, 64, v162
	s_cmp_eq_u32 s24, s1
	s_cbranch_scc1 .LBB0_361
	s_branch .LBB0_342
